# SwiGLU epilogue: adjacent sigmoid chains evaluated in pairs (second on a spare temp) so the s_nop after each transcendental goes away
# speedup vs baseline: 1.0013x; 1.0013x over previous
; __device__ __forceinline__ unsigned cvt_pk_bf16(float lo, float hi) { unsigned r; asm volatile("v_cvt_pk_bf16_f32 %0, %1, %2" : "=v"(r) : "v"(lo), "v"(hi)); return r; }
; __device__ __forceinline__ float fast_sigmoid(float x) { return __builtin_amdgcn_rcpf(1.0f + __builtin_amdgcn_exp2f(-1.44269504089f * x)); }
; #define PG8_BAR __builtin_amdgcn_s_barrier()
;     __device__ __forceinline__ void operator()(const f32x4 (&acc)[2][2][4][2], const Unit& u, int wr, int wc, int fr, int fq) const {
;         const int row0 = u.pm * BM + wr * 64 + fr, col0 = u.pn * HALF + wc * 32 + 8 * fq;
; #pragma unroll
;         for (int ai = 0; ai < 2; ++ai)
; #pragma unroll
;             for (int m = 0; m < 4; ++m) { bf16_t* rowp = O + (size_t)(row0 + ai * HALF + m * 16) * ldc + col0;
;                 float h[8];
; #pragma unroll
;                 for (int n = 0; n < 2; ++n)
; #pragma unroll
;                     for (int j = 0; j < 4; ++j) { const float g = acc[ai][0][m][n][j], up = acc[ai][1][m][n][j]; h[n * 4 + j] = g * fast_sigmoid(g) * up; }
;                 u32x4 w; w.x = cvt_pk_bf16(h[0], h[1]); w.y = cvt_pk_bf16(h[2], h[3]); w.z = cvt_pk_bf16(h[4], h[5]); w.w = cvt_pk_bf16(h[6], h[7]);
;                 *(u32x4*)rowp = w; }
; template <class Epi, class Sched = StaticOrder, bool ALIGN_EPI = true>
; __device__ __forceinline__ void gemm_phase(LAS unsigned char* lds, const Gemm g, const Sched& S, const Epi& E) {
;     ...
;         if constexpr (ALIGN_EPI) { if (wr == 0) PG8_BAR; }
.LBB0_470:
	v_mul_f32_e32 v152, 0xbfb8aa3b, v126
	v_exp_f32_e32 v152, v152
	v_lshl_or_b32 v148, s1, 7, v145
	v_lshl_add_u32 v147, s0, 8, v1
	v_ashrrev_i32_e32 v149, 31, v148
	v_add_f32_e32 v152, 1.0, v152
	v_rcp_f32_e32 v152, v152
	v_mov_b64_e32 v[142:143], s[94:95]
	v_mad_i64_i32 v[150:151], s[0:1], v147, s76, v[142:143]
	v_mul_f32_e32 v126, v126, v152
	v_mul_f32_e32 v122, v126, v122
	v_mul_f32_e32 v126, 0xbfb8aa3b, v127
	v_exp_f32_e32 v126, v126
	v_readlane_b32 s82, v254, 41
	s_andn2_b64 vcc, exec, s[40:41]
	s_mov_b32 s96, s82
	v_add_f32_e32 v126, 1.0, v126
	v_rcp_f32_e32 v126, v126
	v_readlane_b32 s83, v254, 42
	v_mul_f32_e32 v126, v127, v126
	v_mul_f32_e32 v123, v126, v123
	v_mul_f32_e32 v126, 0xbfb8aa3b, v128
	v_mul_f32_e32 v160, 0xbfb8aa3b, v129
	v_exp_f32_e32 v126, v126
	v_exp_f32_e32 v160, v160
	v_add_f32_e32 v126, 1.0, v126
	v_add_f32_e32 v160, 1.0, v160
	v_rcp_f32_e32 v126, v126
	v_rcp_f32_e32 v160, v160
	v_mul_f32_e32 v126, v128, v126
	v_mul_f32_e32 v160, v129, v160
	v_mul_f32_e32 v124, v126, v124
	v_mul_f32_e32 v125, v160, v125
	v_mul_f32_e32 v126, 0xbfb8aa3b, v118
	v_mul_f32_e32 v161, 0xbfb8aa3b, v119
	v_exp_f32_e32 v126, v126
	v_exp_f32_e32 v161, v161
	v_add_f32_e32 v126, 1.0, v126
	v_add_f32_e32 v161, 1.0, v161
	v_rcp_f32_e32 v126, v126
	v_rcp_f32_e32 v161, v161
	v_mul_f32_e32 v118, v118, v126
	v_mul_f32_e32 v161, v119, v161
	v_mul_f32_e32 v118, v118, v114
	v_mul_f32_e32 v119, v161, v115
	v_mul_f32_e32 v114, 0xbfb8aa3b, v120
	v_exp_f32_e32 v114, v114
	s_nop 0
	v_add_f32_e32 v114, 1.0, v114
	v_rcp_f32_e32 v114, v114
	s_nop 0
	v_mul_f32_e32 v114, v120, v114
	v_mul_f32_e32 v126, v114, v116
	v_mul_f32_e32 v114, 0xbfb8aa3b, v121
	v_exp_f32_e32 v114, v114
	v_cvt_pk_bf16_f32 v116, v122, v123
	s_nop 0
	v_add_f32_e32 v114, 1.0, v114
	v_rcp_f32_e32 v114, v114
	s_nop 0
	v_mul_f32_e32 v114, v121, v114
	v_mul_f32_e32 v127, v114, v117
	v_lshlrev_b64 v[114:115], 1, v[148:149]
	v_lshl_add_u64 v[120:121], v[150:151], 0, v[114:115]
	v_cvt_pk_bf16_f32 v117, v124, v125
	v_cvt_pk_bf16_f32 v118, v118, v119
	v_cvt_pk_bf16_f32 v119, v126, v127
	global_store_dwordx4 v[120:121], v[116:119], off
	s_cmp_eq_u64 s[12:13], 0
	s_cbranch_scc1 .Lmy_al_467
	s_barrier
.Lmy_al_467:
	s_nop 1
	v_mul_f32_e32 v118, 0xbfb8aa3b, v110
	v_exp_f32_e32 v118, v118
	v_or_b32_e32 v116, 16, v147
	v_mad_i64_i32 v[116:117], s[0:1], v116, s76, v[142:143]
	v_add_f32_e32 v118, 1.0, v118
	v_rcp_f32_e32 v118, v118
	s_nop 0
	v_mul_f32_e32 v110, v110, v118
	v_mul_f32_e32 v106, v110, v106
	v_mul_f32_e32 v110, 0xbfb8aa3b, v111
	v_mul_f32_e32 v160, 0xbfb8aa3b, v112
	v_exp_f32_e32 v110, v110
	v_exp_f32_e32 v160, v160
	v_add_f32_e32 v110, 1.0, v110
	v_add_f32_e32 v160, 1.0, v160
	v_rcp_f32_e32 v110, v110
	v_rcp_f32_e32 v160, v160
	v_mul_f32_e32 v110, v111, v110
	v_mul_f32_e32 v160, v112, v160
	v_mul_f32_e32 v107, v110, v107
	v_mul_f32_e32 v108, v160, v108
	v_mul_f32_e32 v110, 0xbfb8aa3b, v113
	v_exp_f32_e32 v110, v110
	s_nop 0
	v_add_f32_e32 v110, 1.0, v110
	v_rcp_f32_e32 v110, v110
	s_nop 0
	v_mul_f32_e32 v110, v113, v110
	v_mul_f32_e32 v109, v110, v109
	v_mul_f32_e32 v110, 0xbfb8aa3b, v102
	v_mul_f32_e32 v161, 0xbfb8aa3b, v103
	v_exp_f32_e32 v110, v110
	v_exp_f32_e32 v161, v161
	v_add_f32_e32 v110, 1.0, v110
	v_add_f32_e32 v161, 1.0, v161
	v_rcp_f32_e32 v110, v110
	v_rcp_f32_e32 v161, v161
	v_mul_f32_e32 v102, v102, v110
	v_mul_f32_e32 v161, v103, v161
	v_mul_f32_e32 v110, v102, v98
	v_mul_f32_e32 v111, v161, v99
	v_mul_f32_e32 v98, 0xbfb8aa3b, v104
	v_exp_f32_e32 v98, v98
	v_lshl_add_u64 v[102:103], v[116:117], 0, v[114:115]
	v_add_f32_e32 v98, 1.0, v98
	v_rcp_f32_e32 v98, v98
	s_nop 0
	v_mul_f32_e32 v98, v104, v98
	v_mul_f32_e32 v104, v98, v100
	v_mul_f32_e32 v98, 0xbfb8aa3b, v105
	v_exp_f32_e32 v98, v98
	s_nop 0
	v_add_f32_e32 v98, 1.0, v98
	v_rcp_f32_e32 v98, v98
	s_nop 0
	v_mul_f32_e32 v98, v105, v98
	v_mul_f32_e32 v101, v98, v101
	v_cvt_pk_bf16_f32 v98, v106, v107
	v_cvt_pk_bf16_f32 v99, v108, v109
	v_cvt_pk_bf16_f32 v100, v110, v111
	v_cvt_pk_bf16_f32 v101, v104, v101
	global_store_dwordx4 v[102:103], v[98:101], off
	s_nop 1
	v_mul_f32_e32 v100, 0xbfb8aa3b, v94
	v_exp_f32_e32 v100, v100
	v_or_b32_e32 v98, 32, v147
	v_mad_i64_i32 v[98:99], s[0:1], v98, s76, v[142:143]
	v_add_f32_e32 v100, 1.0, v100
	v_rcp_f32_e32 v100, v100
	s_nop 0
	v_mul_f32_e32 v94, v94, v100
	v_mul_f32_e32 v90, v94, v90
	v_mul_f32_e32 v94, 0xbfb8aa3b, v95
	v_mul_f32_e32 v160, 0xbfb8aa3b, v96
	v_exp_f32_e32 v94, v94
	v_exp_f32_e32 v160, v160
	v_add_f32_e32 v94, 1.0, v94
	v_add_f32_e32 v160, 1.0, v160
	v_rcp_f32_e32 v94, v94
	v_rcp_f32_e32 v160, v160
	v_mul_f32_e32 v94, v95, v94
	v_mul_f32_e32 v160, v96, v160
	v_mul_f32_e32 v91, v94, v91
	v_mul_f32_e32 v92, v160, v92
	v_mul_f32_e32 v94, 0xbfb8aa3b, v97
	v_exp_f32_e32 v94, v94
	s_nop 0
	v_add_f32_e32 v94, 1.0, v94
	v_rcp_f32_e32 v94, v94
	s_nop 0
	v_mul_f32_e32 v94, v97, v94
	v_mul_f32_e32 v93, v94, v93
	v_mul_f32_e32 v94, 0xbfb8aa3b, v86
	v_mul_f32_e32 v161, 0xbfb8aa3b, v87
	v_exp_f32_e32 v94, v94
	v_exp_f32_e32 v161, v161
	v_add_f32_e32 v94, 1.0, v94
	v_add_f32_e32 v161, 1.0, v161
	v_rcp_f32_e32 v94, v94
	v_rcp_f32_e32 v161, v161
	v_mul_f32_e32 v86, v86, v94
	v_mul_f32_e32 v161, v87, v161
	v_mul_f32_e32 v94, v86, v82
	v_mul_f32_e32 v95, v161, v83
	v_mul_f32_e32 v82, 0xbfb8aa3b, v88
	v_exp_f32_e32 v82, v82
	v_lshl_add_u64 v[86:87], v[98:99], 0, v[114:115]
	v_add_f32_e32 v82, 1.0, v82
	v_rcp_f32_e32 v82, v82
	s_nop 0
	v_mul_f32_e32 v82, v88, v82
	v_mul_f32_e32 v88, v82, v84
	v_mul_f32_e32 v82, 0xbfb8aa3b, v89
	v_exp_f32_e32 v82, v82
	s_nop 0
	v_add_f32_e32 v82, 1.0, v82
	v_rcp_f32_e32 v82, v82
	s_nop 0
	v_mul_f32_e32 v82, v89, v82
	v_mul_f32_e32 v85, v82, v85
; __device__ __forceinline__ unsigned cvt_pk_bf16(float lo, float hi) { unsigned r; asm volatile("v_cvt_pk_bf16_f32 %0, %1, %2" : "=v"(r) : "v"(lo), "v"(hi)); return r; }
; __device__ __forceinline__ float fast_sigmoid(float x) { return __builtin_amdgcn_rcpf(1.0f + __builtin_amdgcn_exp2f(-1.44269504089f * x)); }
;     __device__ __forceinline__ void operator()(const f32x4 (&acc)[2][2][4][2], const Unit& u, int wr, int wc, int fr, int fq) const {
;     ...
;         for (int ai = 0; ai < 2; ++ai)
; #pragma unroll
;             for (int m = 0; m < 4; ++m) { bf16_t* rowp = O + (size_t)(row0 + ai * HALF + m * 16) * ldc + col0;
;                 float h[8];
; #pragma unroll
;                 for (int n = 0; n < 2; ++n)
; #pragma unroll
;                     for (int j = 0; j < 4; ++j) { const float g = acc[ai][0][m][n][j], up = acc[ai][1][m][n][j]; h[n * 4 + j] = g * fast_sigmoid(g) * up; }
;                 u32x4 w; w.x = cvt_pk_bf16(h[0], h[1]); w.y = cvt_pk_bf16(h[2], h[3]); w.z = cvt_pk_bf16(h[4], h[5]); w.w = cvt_pk_bf16(h[6], h[7]);
;                 *(u32x4*)rowp = w; }
	v_cvt_pk_bf16_f32 v82, v90, v91
	v_cvt_pk_bf16_f32 v83, v92, v93
	v_cvt_pk_bf16_f32 v84, v94, v95
	v_cvt_pk_bf16_f32 v85, v88, v85
	global_store_dwordx4 v[86:87], v[82:85], off
	s_nop 1
	v_mul_f32_e32 v84, 0xbfb8aa3b, v78
	v_exp_f32_e32 v84, v84
	v_or_b32_e32 v82, 48, v147
	v_mad_i64_i32 v[82:83], s[0:1], v82, s76, v[142:143]
	v_add_f32_e32 v84, 1.0, v84
	v_rcp_f32_e32 v84, v84
	s_nop 0
	v_mul_f32_e32 v78, v78, v84
	v_mul_f32_e32 v74, v78, v74
	v_mul_f32_e32 v78, 0xbfb8aa3b, v79
	v_mul_f32_e32 v160, 0xbfb8aa3b, v80
	v_exp_f32_e32 v78, v78
	v_exp_f32_e32 v160, v160
	v_add_f32_e32 v78, 1.0, v78
	v_add_f32_e32 v160, 1.0, v160
	v_rcp_f32_e32 v78, v78
	v_rcp_f32_e32 v160, v160
	v_mul_f32_e32 v78, v79, v78
	v_mul_f32_e32 v160, v80, v160
	v_mul_f32_e32 v75, v78, v75
	v_mul_f32_e32 v76, v160, v76
	v_mul_f32_e32 v78, 0xbfb8aa3b, v81
	v_exp_f32_e32 v78, v78
	s_nop 0
	v_add_f32_e32 v78, 1.0, v78
	v_rcp_f32_e32 v78, v78
	s_nop 0
	v_mul_f32_e32 v78, v81, v78
	v_mul_f32_e32 v77, v78, v77
	v_mul_f32_e32 v78, 0xbfb8aa3b, v70
	v_mul_f32_e32 v161, 0xbfb8aa3b, v71
	v_exp_f32_e32 v78, v78
	v_exp_f32_e32 v161, v161
	v_add_f32_e32 v78, 1.0, v78
	v_add_f32_e32 v161, 1.0, v161
	v_rcp_f32_e32 v78, v78
	v_rcp_f32_e32 v161, v161
	v_mul_f32_e32 v70, v70, v78
	v_mul_f32_e32 v161, v71, v161
	v_mul_f32_e32 v78, v70, v66
	v_mul_f32_e32 v79, v161, v67
	v_mul_f32_e32 v66, 0xbfb8aa3b, v72
	v_exp_f32_e32 v66, v66
	v_lshl_add_u64 v[70:71], v[82:83], 0, v[114:115]
	v_add_f32_e32 v66, 1.0, v66
	v_rcp_f32_e32 v66, v66
	s_nop 0
	v_mul_f32_e32 v66, v72, v66
	v_mul_f32_e32 v72, v66, v68
	v_mul_f32_e32 v66, 0xbfb8aa3b, v73
	v_exp_f32_e32 v66, v66
	s_nop 0
	v_add_f32_e32 v66, 1.0, v66
	v_rcp_f32_e32 v66, v66
	s_nop 0
	v_mul_f32_e32 v66, v73, v66
	v_mul_f32_e32 v69, v66, v69
	v_cvt_pk_bf16_f32 v66, v74, v75
	v_cvt_pk_bf16_f32 v67, v76, v77
	v_cvt_pk_bf16_f32 v68, v78, v79
	v_cvt_pk_bf16_f32 v69, v72, v69
	global_store_dwordx4 v[70:71], v[66:69], off
	s_nop 1
	v_mul_f32_e32 v68, 0xbfb8aa3b, v62
	v_exp_f32_e32 v68, v68
	v_add_u32_e32 v66, 0x80, v147
	v_mad_i64_i32 v[66:67], s[0:1], v66, s76, v[142:143]
	v_add_f32_e32 v68, 1.0, v68
	v_rcp_f32_e32 v68, v68
	s_nop 0
	v_mul_f32_e32 v62, v62, v68
	v_mul_f32_e32 v58, v62, v58
	v_mul_f32_e32 v62, 0xbfb8aa3b, v63
	v_mul_f32_e32 v160, 0xbfb8aa3b, v64
	v_exp_f32_e32 v62, v62
	v_exp_f32_e32 v160, v160
	v_add_f32_e32 v62, 1.0, v62
	v_add_f32_e32 v160, 1.0, v160
	v_rcp_f32_e32 v62, v62
	v_rcp_f32_e32 v160, v160
	v_mul_f32_e32 v62, v63, v62
	v_mul_f32_e32 v160, v64, v160
	v_mul_f32_e32 v59, v62, v59
	v_mul_f32_e32 v60, v160, v60
	v_mul_f32_e32 v62, 0xbfb8aa3b, v65
	v_exp_f32_e32 v62, v62
	s_nop 0
	v_add_f32_e32 v62, 1.0, v62
	v_rcp_f32_e32 v62, v62
	s_nop 0
	v_mul_f32_e32 v62, v65, v62
	v_mul_f32_e32 v61, v62, v61
	v_mul_f32_e32 v62, 0xbfb8aa3b, v54
	v_mul_f32_e32 v161, 0xbfb8aa3b, v55
	v_exp_f32_e32 v62, v62
	v_exp_f32_e32 v161, v161
	v_add_f32_e32 v62, 1.0, v62
	v_add_f32_e32 v161, 1.0, v161
	v_rcp_f32_e32 v62, v62
	v_rcp_f32_e32 v161, v161
	v_mul_f32_e32 v54, v54, v62
	v_mul_f32_e32 v161, v55, v161
	v_mul_f32_e32 v62, v54, v50
	v_mul_f32_e32 v63, v161, v51
	v_mul_f32_e32 v50, 0xbfb8aa3b, v56
	v_exp_f32_e32 v50, v50
	v_lshl_add_u64 v[54:55], v[66:67], 0, v[114:115]
	v_add_f32_e32 v50, 1.0, v50
	v_rcp_f32_e32 v50, v50
	s_nop 0
	v_mul_f32_e32 v50, v56, v50
	v_mul_f32_e32 v56, v50, v52
	v_mul_f32_e32 v50, 0xbfb8aa3b, v57
	v_exp_f32_e32 v50, v50
	s_nop 0
	v_add_f32_e32 v50, 1.0, v50
	v_rcp_f32_e32 v50, v50
	s_nop 0
	v_mul_f32_e32 v50, v57, v50
	v_mul_f32_e32 v53, v50, v53
	v_cvt_pk_bf16_f32 v50, v58, v59
	v_cvt_pk_bf16_f32 v51, v60, v61
	v_cvt_pk_bf16_f32 v52, v62, v63
	v_cvt_pk_bf16_f32 v53, v56, v53
	global_store_dwordx4 v[54:55], v[50:53], off
	s_nop 1
	v_mul_f32_e32 v52, 0xbfb8aa3b, v46
	v_exp_f32_e32 v52, v52
	v_add_u32_e32 v50, 0x90, v147
	v_mad_i64_i32 v[50:51], s[0:1], v50, s76, v[142:143]
	v_add_f32_e32 v52, 1.0, v52
	v_rcp_f32_e32 v52, v52
	s_nop 0
	v_mul_f32_e32 v46, v46, v52
	v_mul_f32_e32 v42, v46, v42
	v_mul_f32_e32 v46, 0xbfb8aa3b, v47
	v_mul_f32_e32 v160, 0xbfb8aa3b, v48
	v_exp_f32_e32 v46, v46
	v_exp_f32_e32 v160, v160
	v_add_f32_e32 v46, 1.0, v46
	v_add_f32_e32 v160, 1.0, v160
	v_rcp_f32_e32 v46, v46
	v_rcp_f32_e32 v160, v160
	v_mul_f32_e32 v46, v47, v46
	v_mul_f32_e32 v160, v48, v160
	v_mul_f32_e32 v43, v46, v43
	v_mul_f32_e32 v44, v160, v44
	v_mul_f32_e32 v46, 0xbfb8aa3b, v49
	v_exp_f32_e32 v46, v46
	s_nop 0
	v_add_f32_e32 v46, 1.0, v46
	v_rcp_f32_e32 v46, v46
	s_nop 0
	v_mul_f32_e32 v46, v49, v46
; __device__ __forceinline__ unsigned cvt_pk_bf16(float lo, float hi) { unsigned r; asm volatile("v_cvt_pk_bf16_f32 %0, %1, %2" : "=v"(r) : "v"(lo), "v"(hi)); return r; }
; __device__ __forceinline__ float fast_sigmoid(float x) { return __builtin_amdgcn_rcpf(1.0f + __builtin_amdgcn_exp2f(-1.44269504089f * x)); }
;     __device__ __forceinline__ void operator()(const f32x4 (&acc)[2][2][4][2], const Unit& u, int wr, int wc, int fr, int fq) const {
;     ...
;         for (int ai = 0; ai < 2; ++ai)
; #pragma unroll
;             for (int m = 0; m < 4; ++m) { bf16_t* rowp = O + (size_t)(row0 + ai * HALF + m * 16) * ldc + col0;
;                 float h[8];
; #pragma unroll
;                 for (int n = 0; n < 2; ++n)
; #pragma unroll
;                     for (int j = 0; j < 4; ++j) { const float g = acc[ai][0][m][n][j], up = acc[ai][1][m][n][j]; h[n * 4 + j] = g * fast_sigmoid(g) * up; }
;                 u32x4 w; w.x = cvt_pk_bf16(h[0], h[1]); w.y = cvt_pk_bf16(h[2], h[3]); w.z = cvt_pk_bf16(h[4], h[5]); w.w = cvt_pk_bf16(h[6], h[7]);
;                 *(u32x4*)rowp = w; }
	v_mul_f32_e32 v45, v46, v45
	v_mul_f32_e32 v46, 0xbfb8aa3b, v38
	v_mul_f32_e32 v161, 0xbfb8aa3b, v39
	v_exp_f32_e32 v46, v46
	v_exp_f32_e32 v161, v161
	v_add_f32_e32 v46, 1.0, v46
	v_add_f32_e32 v161, 1.0, v161
	v_rcp_f32_e32 v46, v46
	v_rcp_f32_e32 v161, v161
	v_mul_f32_e32 v38, v38, v46
	v_mul_f32_e32 v161, v39, v161
	v_mul_f32_e32 v46, v38, v34
	v_mul_f32_e32 v47, v161, v35
	v_mul_f32_e32 v34, 0xbfb8aa3b, v40
	v_exp_f32_e32 v34, v34
	v_lshl_add_u64 v[38:39], v[50:51], 0, v[114:115]
	v_add_f32_e32 v34, 1.0, v34
	v_rcp_f32_e32 v34, v34
	s_nop 0
	v_mul_f32_e32 v34, v40, v34
	v_mul_f32_e32 v40, v34, v36
	v_mul_f32_e32 v34, 0xbfb8aa3b, v41
	v_exp_f32_e32 v34, v34
	s_nop 0
	v_add_f32_e32 v34, 1.0, v34
	v_rcp_f32_e32 v34, v34
	s_nop 0
	v_mul_f32_e32 v34, v41, v34
	v_mul_f32_e32 v37, v34, v37
	v_cvt_pk_bf16_f32 v34, v42, v43
	v_cvt_pk_bf16_f32 v35, v44, v45
	v_cvt_pk_bf16_f32 v36, v46, v47
	v_cvt_pk_bf16_f32 v37, v40, v37
	global_store_dwordx4 v[38:39], v[34:37], off
	s_nop 1
	v_mul_f32_e32 v36, 0xbfb8aa3b, v30
	v_exp_f32_e32 v36, v36
	v_add_u32_e32 v34, 0xa0, v147
	v_mad_i64_i32 v[34:35], s[0:1], v34, s76, v[142:143]
	v_add_f32_e32 v36, 1.0, v36
	v_rcp_f32_e32 v36, v36
	s_nop 0
	v_mul_f32_e32 v30, v30, v36
	v_mul_f32_e32 v26, v30, v26
	v_mul_f32_e32 v30, 0xbfb8aa3b, v31
	v_mul_f32_e32 v160, 0xbfb8aa3b, v32
	v_exp_f32_e32 v30, v30
	v_exp_f32_e32 v160, v160
	v_add_f32_e32 v30, 1.0, v30
	v_add_f32_e32 v160, 1.0, v160
	v_rcp_f32_e32 v30, v30
	v_rcp_f32_e32 v160, v160
	v_mul_f32_e32 v30, v31, v30
	v_mul_f32_e32 v160, v32, v160
	v_mul_f32_e32 v27, v30, v27
	v_mul_f32_e32 v28, v160, v28
	v_mul_f32_e32 v30, 0xbfb8aa3b, v33
	v_exp_f32_e32 v30, v30
	s_nop 0
	v_add_f32_e32 v30, 1.0, v30
	v_rcp_f32_e32 v30, v30
	s_nop 0
	v_mul_f32_e32 v30, v33, v30
	v_mul_f32_e32 v29, v30, v29
	v_mul_f32_e32 v30, 0xbfb8aa3b, v22
	v_mul_f32_e32 v161, 0xbfb8aa3b, v23
	v_exp_f32_e32 v30, v30
	v_exp_f32_e32 v161, v161
	v_add_f32_e32 v30, 1.0, v30
	v_add_f32_e32 v161, 1.0, v161
	v_rcp_f32_e32 v30, v30
	v_rcp_f32_e32 v161, v161
	v_mul_f32_e32 v22, v22, v30
	v_mul_f32_e32 v161, v23, v161
	v_mul_f32_e32 v30, v22, v18
	v_mul_f32_e32 v31, v161, v19
	v_mul_f32_e32 v18, 0xbfb8aa3b, v24
	v_exp_f32_e32 v18, v18
	v_lshl_add_u64 v[22:23], v[34:35], 0, v[114:115]
	v_add_f32_e32 v18, 1.0, v18
	v_rcp_f32_e32 v18, v18
	s_nop 0
	v_mul_f32_e32 v18, v24, v18
	v_mul_f32_e32 v24, v18, v20
	v_mul_f32_e32 v18, 0xbfb8aa3b, v25
	v_exp_f32_e32 v18, v18
	s_nop 0
	v_add_f32_e32 v18, 1.0, v18
	v_rcp_f32_e32 v18, v18
	s_nop 0
	v_mul_f32_e32 v18, v25, v18
	v_mul_f32_e32 v21, v18, v21
	v_cvt_pk_bf16_f32 v18, v26, v27
	v_cvt_pk_bf16_f32 v19, v28, v29
	v_cvt_pk_bf16_f32 v20, v30, v31
	v_cvt_pk_bf16_f32 v21, v24, v21
	global_store_dwordx4 v[22:23], v[18:21], off
	s_nop 1
	v_mul_f32_e32 v20, 0xbfb8aa3b, v14
	v_exp_f32_e32 v20, v20
	v_add_u32_e32 v18, 0xb0, v147
	v_mad_i64_i32 v[18:19], s[0:1], v18, s76, v[142:143]
	v_add_f32_e32 v20, 1.0, v20
	v_rcp_f32_e32 v20, v20
	s_mov_b64 s[0:1], -1
	v_mul_f32_e32 v14, v14, v20
	v_mul_f32_e32 v10, v14, v10
	v_mul_f32_e32 v14, 0xbfb8aa3b, v15
	v_mul_f32_e32 v160, 0xbfb8aa3b, v16
	v_exp_f32_e32 v14, v14
	v_exp_f32_e32 v160, v160
	v_add_f32_e32 v14, 1.0, v14
	v_add_f32_e32 v160, 1.0, v160
	v_rcp_f32_e32 v14, v14
	v_rcp_f32_e32 v160, v160
	v_mul_f32_e32 v14, v15, v14
	v_mul_f32_e32 v160, v16, v160
	v_mul_f32_e32 v11, v14, v11
	v_mul_f32_e32 v12, v160, v12
	v_mul_f32_e32 v14, 0xbfb8aa3b, v17
	v_exp_f32_e32 v14, v14
	s_nop 0
	v_add_f32_e32 v14, 1.0, v14
	v_rcp_f32_e32 v14, v14
	s_nop 0
	v_mul_f32_e32 v14, v17, v14
	v_mul_f32_e32 v13, v14, v13
	v_mul_f32_e32 v14, 0xbfb8aa3b, v6
	v_mul_f32_e32 v161, 0xbfb8aa3b, v7
	v_exp_f32_e32 v14, v14
	v_exp_f32_e32 v161, v161
	v_add_f32_e32 v14, 1.0, v14
	v_add_f32_e32 v161, 1.0, v161
	v_rcp_f32_e32 v14, v14
	v_rcp_f32_e32 v161, v161
	v_mul_f32_e32 v6, v6, v14
	v_mul_f32_e32 v161, v7, v161
	v_mul_f32_e32 v14, v6, v2
	v_mul_f32_e32 v15, v161, v3
	v_mul_f32_e32 v2, 0xbfb8aa3b, v8
	v_exp_f32_e32 v2, v2
	v_lshl_add_u64 v[6:7], v[18:19], 0, v[114:115]
	v_add_f32_e32 v2, 1.0, v2
	v_rcp_f32_e32 v2, v2
	s_nop 0
	v_mul_f32_e32 v2, v8, v2
	v_mul_f32_e32 v8, v2, v4
	v_mul_f32_e32 v2, 0xbfb8aa3b, v9
	v_exp_f32_e32 v2, v2
	s_nop 0
	v_add_f32_e32 v2, 1.0, v2
	v_rcp_f32_e32 v2, v2
	s_nop 0
	v_mul_f32_e32 v2, v9, v2
	v_mul_f32_e32 v5, v2, v5
	v_cvt_pk_bf16_f32 v2, v10, v11
	v_cvt_pk_bf16_f32 v3, v12, v13
	v_cvt_pk_bf16_f32 v4, v14, v15
	v_cvt_pk_bf16_f32 v5, v8, v5
	global_store_dwordx4 v[6:7], v[2:5], off
	s_cbranch_vccnz .LBB0_463
	s_branch .LBB0_462
